# GEMM units: accumulator zeroing with 64-bit moves (half the instructions)
# speedup vs baseline: 1.0080x; 1.0080x over previous
; template <class Epi, bool ALIGN_EPI, bool SP2>
; __device__ __forceinline__ void gemm_phase(LAS unsigned char* lds, const Gemm g, const Sched& S, const Epi& E) {
;     ...
;         const bool has_next = S.next(ui + 1, nxt);
;         const int nt = cur.nt;
;         const char* nA = has_next ? (const char*)g.A + (size_t)nxt.pm * tstep + (size_t)nxt.k0 * kstep : cA; const char* nB = has_next ? (const char*)g.Bt + (size_t)nxt.pn * tstep + (size_t)nxt.k0 * kstep : cB;
;         for (int t = 0; t < nt; t += 2) {
;             const bool last = (t == nt - 2);
;             const char* a1 = cA + (size_t)(t + 1) * kstep;
;             const char* a2 = last ? nA : cA + (size_t)(t + 2) * kstep; const char* b2 = last ? nB : cB + (size_t)(t + 2) * kstep;
;             const char* a3 = a2 + kstep; const char* b3 = b2 + kstep;
;     ...
; #pragma unroll
;         for (int a = 0; a < 2; ++a)
; #pragma unroll
;             for (int b = 0; b < 2; ++b)
; #pragma unroll
;                 for (int m = 0; m < 4; ++m)
; #pragma unroll
;                     for (int n = 0; n < 2; ++n) acc[a][b][m][n] = (f32x4){0.f, 0.f, 0.f, 0.f};
.LBB0_44:
	s_ashr_i32 s15, s14, 31
	s_lshl_b64 s[42:43], s[14:15], 20
	v_readlane_b32 s2, v253, 4
	v_readlane_b32 s3, v253, 5
	s_add_u32 s42, s2, s42
	s_addc_u32 s43, s3, s43
	s_ashr_i32 s13, s12, 31
	s_lshl_b64 s[48:49], s[12:13], 20
	s_add_u32 s48, s51, s48
	s_addc_u32 s49, s56, s49
	s_cmp_lt_i32 s68, 1
	s_cbranch_scc1 .LBB0_52
	s_and_b64 s[24:25], s[24:25], exec
	s_cselect_b32 s13, s43, s21
	s_cselect_b32 s15, s42, s20
	s_cselect_b32 s17, s49, s23
	s_cselect_b32 s24, s48, s22
	s_add_i32 s25, s68, -2
	s_add_u32 s54, s20, 0x80080
	s_addc_u32 s55, s21, 0
	s_add_u32 s69, s22, 0x100
	v_mov_b32_e32 v0, 0
	s_addc_u32 s70, s23, 0
	s_mov_b32 s20, 0
	v_mov_b32_e32 v1, v0
	v_mov_b64_e32 v[2:3], 0
	v_mov_b64_e32 v[8:9], 0
	v_mov_b64_e32 v[10:11], 0
	v_mov_b64_e32 v[16:17], 0
	v_mov_b64_e32 v[18:19], 0
	v_mov_b64_e32 v[24:25], 0
	v_mov_b64_e32 v[26:27], 0
	v_mov_b64_e32 v[32:33], 0
	v_mov_b64_e32 v[34:35], 0
	v_mov_b64_e32 v[40:41], 0
	v_mov_b64_e32 v[42:43], 0
	v_mov_b64_e32 v[48:49], 0
	v_mov_b64_e32 v[50:51], 0
	v_mov_b64_e32 v[56:57], 0
	v_mov_b64_e32 v[58:59], 0
	v_mov_b64_e32 v[4:5], 0
	v_mov_b64_e32 v[6:7], 0
	v_mov_b64_e32 v[12:13], 0
	v_mov_b64_e32 v[14:15], 0
	v_mov_b64_e32 v[20:21], 0
	v_mov_b64_e32 v[22:23], 0
	v_mov_b64_e32 v[28:29], 0
	v_mov_b64_e32 v[30:31], 0
	v_mov_b64_e32 v[36:37], 0
	v_mov_b64_e32 v[38:39], 0
	v_mov_b64_e32 v[44:45], 0
	v_mov_b64_e32 v[46:47], 0
	v_mov_b64_e32 v[52:53], 0
	v_mov_b64_e32 v[54:55], 0
	v_mov_b64_e32 v[60:61], 0
	v_mov_b64_e32 v[62:63], 0
	v_mov_b64_e32 v[64:65], 0
	v_mov_b64_e32 v[66:67], 0
	v_mov_b64_e32 v[72:73], 0
	v_mov_b64_e32 v[74:75], 0
	v_mov_b64_e32 v[80:81], 0
	v_mov_b64_e32 v[82:83], 0
	v_mov_b64_e32 v[88:89], 0
	v_mov_b64_e32 v[90:91], 0
	v_mov_b64_e32 v[102:103], 0
	v_mov_b64_e32 v[104:105], 0
	v_mov_b64_e32 v[110:111], 0
	v_mov_b64_e32 v[112:113], 0
	v_mov_b64_e32 v[118:119], 0
	v_mov_b64_e32 v[120:121], 0
	v_mov_b64_e32 v[126:127], 0
	v_mov_b64_e32 v[128:129], 0
	v_mov_b64_e32 v[68:69], 0
	v_mov_b64_e32 v[70:71], 0
	v_mov_b64_e32 v[76:77], 0
	v_mov_b64_e32 v[78:79], 0
	v_mov_b64_e32 v[84:85], 0
	v_mov_b64_e32 v[86:87], 0
	v_mov_b64_e32 v[92:93], 0
	v_mov_b64_e32 v[94:95], 0
	v_mov_b64_e32 v[106:107], 0
	v_mov_b64_e32 v[108:109], 0
	v_mov_b64_e32 v[114:115], 0
	v_mov_b64_e32 v[116:117], 0
	v_mov_b64_e32 v[122:123], 0
	v_mov_b64_e32 v[124:125], 0
	v_mov_b64_e32 v[130:131], 0
	v_mov_b64_e32 v[132:133], 0

; template <class Epi, bool ALIGN_EPI, bool SP2>
; __device__ __forceinline__ void gemm_phase(LAS unsigned char* lds, const Gemm g, const Sched& S, const Epi& E) {
;     ...
; #pragma unroll
;         for (int a = 0; a < 2; ++a)
; #pragma unroll
;             for (int b = 0; b < 2; ++b)
; #pragma unroll
;                 for (int m = 0; m < 4; ++m)
; #pragma unroll
;                     for (int n = 0; n < 2; ++n) acc[a][b][m][n] = (f32x4){0.f, 0.f, 0.f, 0.f};
.LBB0_52:
	v_mov_b32_e32 v133, 0
	v_mov_b32_e32 v132, v133
	v_mov_b64_e32 v[130:131], 0
	v_mov_b64_e32 v[124:125], 0
	v_mov_b64_e32 v[122:123], 0
	v_mov_b64_e32 v[116:117], 0
	v_mov_b64_e32 v[114:115], 0
	v_mov_b64_e32 v[108:109], 0
	v_mov_b64_e32 v[106:107], 0
	v_mov_b64_e32 v[94:95], 0
	v_mov_b64_e32 v[92:93], 0
	v_mov_b64_e32 v[86:87], 0
	v_mov_b64_e32 v[84:85], 0
	v_mov_b64_e32 v[78:79], 0
	v_mov_b64_e32 v[76:77], 0
	v_mov_b64_e32 v[70:71], 0
	v_mov_b64_e32 v[68:69], 0
	v_mov_b64_e32 v[128:129], 0
	v_mov_b64_e32 v[126:127], 0
	v_mov_b64_e32 v[120:121], 0
	v_mov_b64_e32 v[118:119], 0
	v_mov_b64_e32 v[112:113], 0
	v_mov_b64_e32 v[110:111], 0
	v_mov_b64_e32 v[104:105], 0
	v_mov_b64_e32 v[102:103], 0
	v_mov_b64_e32 v[90:91], 0
	v_mov_b64_e32 v[88:89], 0
	v_mov_b64_e32 v[82:83], 0
	v_mov_b64_e32 v[80:81], 0
	v_mov_b64_e32 v[74:75], 0
	v_mov_b64_e32 v[72:73], 0
	v_mov_b64_e32 v[66:67], 0
	v_mov_b64_e32 v[64:65], 0
	v_mov_b64_e32 v[62:63], 0
	v_mov_b64_e32 v[60:61], 0
	v_mov_b64_e32 v[54:55], 0
	v_mov_b64_e32 v[52:53], 0
	v_mov_b64_e32 v[46:47], 0
	v_mov_b64_e32 v[44:45], 0
	v_mov_b64_e32 v[38:39], 0
	v_mov_b64_e32 v[36:37], 0
	v_mov_b64_e32 v[30:31], 0
	v_mov_b64_e32 v[28:29], 0
	v_mov_b64_e32 v[22:23], 0
	v_mov_b64_e32 v[20:21], 0
	v_mov_b64_e32 v[14:15], 0
	v_mov_b64_e32 v[12:13], 0
	v_mov_b64_e32 v[6:7], 0
	v_mov_b64_e32 v[4:5], 0
	v_mov_b64_e32 v[58:59], 0
	v_mov_b64_e32 v[56:57], 0
	v_mov_b64_e32 v[50:51], 0
	v_mov_b64_e32 v[48:49], 0
	v_mov_b64_e32 v[42:43], 0
	v_mov_b64_e32 v[40:41], 0
	v_mov_b64_e32 v[34:35], 0
	v_mov_b64_e32 v[32:33], 0
	v_mov_b64_e32 v[26:27], 0
	v_mov_b64_e32 v[24:25], 0
	v_mov_b64_e32 v[18:19], 0
	v_mov_b64_e32 v[16:17], 0
	v_mov_b64_e32 v[10:11], 0
	v_mov_b64_e32 v[8:9], 0
	v_mov_b64_e32 v[2:3], 0
	v_mov_b64_e32 v[0:1], 0
	s_and_b64 vcc, exec, s[10:11]
	s_cbranch_vccnz .LBB0_48
	s_branch .LBB0_49

; template <class Epi, bool ALIGN_EPI, bool SP2>
; __device__ __forceinline__ void gemm_phase(LAS unsigned char* lds, const Gemm g, const Sched& S, const Epi& E) {
;     ...
; #pragma unroll
;         for (int a = 0; a < 2; ++a)
; #pragma unroll
;             for (int b = 0; b < 2; ++b)
; #pragma unroll
;                 for (int m = 0; m < 4; ++m)
; #pragma unroll
;                     for (int n = 0; n < 2; ++n) acc[a][b][m][n] = (f32x4){0.f, 0.f, 0.f, 0.f};
.LBB0_328:
	s_add_i32 s17, s66, -2
	s_add_u32 s19, s20, 0x100
	v_mov_b32_e32 v0, 0
	s_addc_u32 s45, s21, 0
	s_mov_b32 s22, 0
	v_mov_b32_e32 v1, v0
	v_mov_b64_e32 v[2:3], 0
	v_mov_b64_e32 v[4:5], 0
	v_mov_b64_e32 v[6:7], 0
	v_mov_b64_e32 v[16:17], 0
	v_mov_b64_e32 v[18:19], 0
	v_mov_b64_e32 v[20:21], 0
	v_mov_b64_e32 v[22:23], 0
	v_mov_b64_e32 v[32:33], 0
	v_mov_b64_e32 v[34:35], 0
	v_mov_b64_e32 v[36:37], 0
	v_mov_b64_e32 v[38:39], 0
	v_mov_b64_e32 v[48:49], 0
	v_mov_b64_e32 v[50:51], 0
	v_mov_b64_e32 v[52:53], 0
	v_mov_b64_e32 v[54:55], 0
	v_mov_b64_e32 v[8:9], 0
	v_mov_b64_e32 v[10:11], 0
	v_mov_b64_e32 v[12:13], 0
	v_mov_b64_e32 v[14:15], 0
	v_mov_b64_e32 v[24:25], 0
	v_mov_b64_e32 v[26:27], 0
	v_mov_b64_e32 v[28:29], 0
	v_mov_b64_e32 v[30:31], 0
	v_mov_b64_e32 v[40:41], 0
	v_mov_b64_e32 v[42:43], 0
	v_mov_b64_e32 v[44:45], 0
	v_mov_b64_e32 v[46:47], 0
	v_mov_b64_e32 v[56:57], 0
	v_mov_b64_e32 v[58:59], 0
	v_mov_b64_e32 v[60:61], 0
	v_mov_b64_e32 v[62:63], 0
	v_mov_b64_e32 v[64:65], 0
	v_mov_b64_e32 v[66:67], 0
	v_mov_b64_e32 v[68:69], 0
	v_mov_b64_e32 v[70:71], 0
	v_mov_b64_e32 v[80:81], 0
	v_mov_b64_e32 v[82:83], 0
	v_mov_b64_e32 v[84:85], 0
	v_mov_b64_e32 v[86:87], 0
	v_mov_b64_e32 v[102:103], 0
	v_mov_b64_e32 v[104:105], 0
	v_mov_b64_e32 v[106:107], 0
	v_mov_b64_e32 v[108:109], 0
	v_mov_b64_e32 v[118:119], 0
	v_mov_b64_e32 v[120:121], 0
	v_mov_b64_e32 v[122:123], 0
	v_mov_b64_e32 v[124:125], 0
	v_mov_b64_e32 v[72:73], 0
	v_mov_b64_e32 v[74:75], 0
	v_mov_b64_e32 v[76:77], 0
	v_mov_b64_e32 v[78:79], 0
	v_mov_b64_e32 v[88:89], 0
	v_mov_b64_e32 v[90:91], 0
	v_mov_b64_e32 v[92:93], 0
	v_mov_b64_e32 v[94:95], 0
	v_mov_b64_e32 v[110:111], 0
	v_mov_b64_e32 v[112:113], 0
	v_mov_b64_e32 v[114:115], 0
	v_mov_b64_e32 v[116:117], 0
	v_mov_b64_e32 v[126:127], 0
	v_mov_b64_e32 v[128:129], 0
	v_mov_b64_e32 v[130:131], 0
	v_mov_b64_e32 v[132:133], 0

; template <class Epi, bool ALIGN_EPI, bool SP2>
; __device__ __forceinline__ void gemm_phase(LAS unsigned char* lds, const Gemm g, const Sched& S, const Epi& E) {
;     ...
; #pragma unroll
;         for (int a = 0; a < 2; ++a)
; #pragma unroll
;             for (int b = 0; b < 2; ++b)
; #pragma unroll
;                 for (int m = 0; m < 4; ++m)
; #pragma unroll
;                     for (int n = 0; n < 2; ++n) acc[a][b][m][n] = (f32x4){0.f, 0.f, 0.f, 0.f};
.LBB0_343:
	v_mov_b32_e32 v133, 0
	v_mov_b32_e32 v132, v133
	v_mov_b64_e32 v[130:131], 0
	v_mov_b64_e32 v[128:129], 0
	v_mov_b64_e32 v[126:127], 0
	v_mov_b64_e32 v[116:117], 0
	v_mov_b64_e32 v[114:115], 0
	v_mov_b64_e32 v[112:113], 0
	v_mov_b64_e32 v[110:111], 0
	v_mov_b64_e32 v[94:95], 0
	v_mov_b64_e32 v[92:93], 0
	v_mov_b64_e32 v[90:91], 0
	v_mov_b64_e32 v[88:89], 0
	v_mov_b64_e32 v[78:79], 0
	v_mov_b64_e32 v[76:77], 0
	v_mov_b64_e32 v[74:75], 0
	v_mov_b64_e32 v[72:73], 0
	v_mov_b64_e32 v[124:125], 0
	v_mov_b64_e32 v[122:123], 0
	v_mov_b64_e32 v[120:121], 0
	v_mov_b64_e32 v[118:119], 0
	v_mov_b64_e32 v[108:109], 0
	v_mov_b64_e32 v[106:107], 0
	v_mov_b64_e32 v[104:105], 0
	v_mov_b64_e32 v[102:103], 0
	v_mov_b64_e32 v[86:87], 0
	v_mov_b64_e32 v[84:85], 0
	v_mov_b64_e32 v[82:83], 0
	v_mov_b64_e32 v[80:81], 0
	v_mov_b64_e32 v[70:71], 0
	v_mov_b64_e32 v[68:69], 0
	v_mov_b64_e32 v[66:67], 0
	v_mov_b64_e32 v[64:65], 0
	v_mov_b64_e32 v[62:63], 0
	v_mov_b64_e32 v[60:61], 0
	v_mov_b64_e32 v[58:59], 0
	v_mov_b64_e32 v[56:57], 0
	v_mov_b64_e32 v[46:47], 0
	v_mov_b64_e32 v[44:45], 0
	v_mov_b64_e32 v[42:43], 0
	v_mov_b64_e32 v[40:41], 0
	v_mov_b64_e32 v[30:31], 0
	v_mov_b64_e32 v[28:29], 0
	v_mov_b64_e32 v[26:27], 0
	v_mov_b64_e32 v[24:25], 0
	v_mov_b64_e32 v[14:15], 0
	v_mov_b64_e32 v[12:13], 0
	v_mov_b64_e32 v[10:11], 0
	v_mov_b64_e32 v[8:9], 0
	v_mov_b64_e32 v[54:55], 0
	v_mov_b64_e32 v[52:53], 0
	v_mov_b64_e32 v[50:51], 0
	v_mov_b64_e32 v[48:49], 0
	v_mov_b64_e32 v[38:39], 0
	v_mov_b64_e32 v[36:37], 0
	v_mov_b64_e32 v[34:35], 0
	v_mov_b64_e32 v[32:33], 0
	v_mov_b64_e32 v[22:23], 0
	v_mov_b64_e32 v[20:21], 0
	v_mov_b64_e32 v[18:19], 0
	v_mov_b64_e32 v[16:17], 0
	v_mov_b64_e32 v[6:7], 0
	v_mov_b64_e32 v[4:5], 0
	v_mov_b64_e32 v[2:3], 0
	v_mov_b64_e32 v[0:1], 0
	s_and_b64 vcc, exec, s[14:15]
	s_cbranch_vccnz .LBB0_331
	s_branch .LBB0_332

; template <class Epi, bool ALIGN_EPI, bool SP2>
; __device__ __forceinline__ void gemm_phase(LAS unsigned char* lds, const Gemm g, const Sched& S, const Epi& E) {
;     ...
;         const bool has_next = S.next(ui + 1, nxt);
;         const int nt = cur.nt;
;         const char* nA = has_next ? (const char*)g.A + (size_t)nxt.pm * tstep + (size_t)nxt.k0 * kstep : cA; const char* nB = has_next ? (const char*)g.Bt + (size_t)nxt.pn * tstep + (size_t)nxt.k0 * kstep : cB;
;         for (int t = 0; t < nt; t += 2) {
;             const bool last = (t == nt - 2);
;             const char* a1 = cA + (size_t)(t + 1) * kstep;
;             const char* a2 = last ? nA : cA + (size_t)(t + 2) * kstep; const char* b2 = last ? nB : cB + (size_t)(t + 2) * kstep;
;             const char* a3 = a2 + kstep; const char* b3 = b2 + kstep;
;     ...
; #pragma unroll
;         for (int a = 0; a < 2; ++a)
; #pragma unroll
;             for (int b = 0; b < 2; ++b)
; #pragma unroll
;                 for (int m = 0; m < 4; ++m)
; #pragma unroll
;                     for (int n = 0; n < 2; ++n) acc[a][b][m][n] = (f32x4){0.f, 0.f, 0.f, 0.f};
.LBB0_583:
	s_ashr_i32 s19, s18, 31
	s_lshl_b64 s[12:13], s[18:19], 20
	v_readlane_b32 s2, v253, 4
	v_readlane_b32 s3, v253, 5
	s_add_u32 s12, s2, s12
	s_addc_u32 s13, s3, s13
	s_ashr_i32 s17, s16, 31
	s_lshl_b64 s[14:15], s[16:17], 20
	s_add_u32 s14, s80, s14
	s_addc_u32 s15, s81, s15
	s_cmp_lt_i32 s36, 1
	s_cbranch_scc1 .LBB0_638
	s_and_b64 s[24:25], s[24:25], exec
	s_cselect_b32 s7, s13, s21
	s_cselect_b32 s9, s12, s20
	s_cselect_b32 s11, s15, s23
	s_cselect_b32 s17, s14, s22
	s_add_i32 s19, s36, -2
	s_add_u32 s44, s20, 0x80080
	s_addc_u32 s45, s21, 0
	s_add_u32 s24, s22, 0x100
	v_mov_b32_e32 v0, 0
	s_addc_u32 s25, s23, 0
	s_mov_b32 s20, 0
	v_mov_b32_e32 v1, v0
	v_mov_b64_e32 v[2:3], 0
	v_mov_b64_e32 v[4:5], 0
	v_mov_b64_e32 v[6:7], 0
	v_mov_b64_e32 v[16:17], 0
	v_mov_b64_e32 v[18:19], 0
	v_mov_b64_e32 v[20:21], 0
	v_mov_b64_e32 v[22:23], 0
	v_mov_b64_e32 v[32:33], 0
	v_mov_b64_e32 v[34:35], 0
	v_mov_b64_e32 v[36:37], 0
	v_mov_b64_e32 v[38:39], 0
	v_mov_b64_e32 v[48:49], 0
	v_mov_b64_e32 v[50:51], 0
	v_mov_b64_e32 v[52:53], 0
	v_mov_b64_e32 v[54:55], 0
	v_mov_b64_e32 v[8:9], 0
	v_mov_b64_e32 v[10:11], 0
	v_mov_b64_e32 v[12:13], 0
	v_mov_b64_e32 v[14:15], 0
	v_mov_b64_e32 v[24:25], 0
	v_mov_b64_e32 v[26:27], 0
	v_mov_b64_e32 v[28:29], 0
	v_mov_b64_e32 v[30:31], 0
	v_mov_b64_e32 v[40:41], 0
	v_mov_b64_e32 v[42:43], 0
	v_mov_b64_e32 v[44:45], 0
	v_mov_b64_e32 v[46:47], 0
	v_mov_b64_e32 v[56:57], 0
	v_mov_b64_e32 v[58:59], 0
	v_mov_b64_e32 v[60:61], 0
	v_mov_b64_e32 v[62:63], 0
	v_mov_b64_e32 v[64:65], 0
	v_mov_b64_e32 v[66:67], 0
	v_mov_b64_e32 v[68:69], 0
	v_mov_b64_e32 v[70:71], 0
	v_mov_b64_e32 v[80:81], 0
	v_mov_b64_e32 v[82:83], 0
	v_mov_b64_e32 v[84:85], 0
	v_mov_b64_e32 v[86:87], 0
	v_mov_b64_e32 v[104:105], 0
	v_mov_b64_e32 v[106:107], 0
	v_mov_b64_e32 v[108:109], 0
	v_mov_b64_e32 v[110:111], 0
	v_mov_b64_e32 v[120:121], 0
	v_mov_b64_e32 v[122:123], 0
	v_mov_b64_e32 v[124:125], 0
	v_mov_b64_e32 v[126:127], 0
	v_mov_b64_e32 v[72:73], 0
	v_mov_b64_e32 v[74:75], 0
	v_mov_b64_e32 v[76:77], 0
	v_mov_b64_e32 v[78:79], 0
	v_mov_b64_e32 v[88:89], 0
	v_mov_b64_e32 v[90:91], 0
	v_mov_b64_e32 v[92:93], 0
	v_mov_b64_e32 v[94:95], 0
	v_mov_b64_e32 v[112:113], 0
	v_mov_b64_e32 v[114:115], 0
	v_mov_b64_e32 v[116:117], 0
	v_mov_b64_e32 v[118:119], 0
	v_mov_b64_e32 v[128:129], 0
	v_mov_b64_e32 v[130:131], 0
	v_mov_b64_e32 v[132:133], 0
	v_mov_b64_e32 v[134:135], 0

; template <class Epi, bool ALIGN_EPI, bool SP2>
; __device__ __forceinline__ void gemm_phase(LAS unsigned char* lds, const Gemm g, const Sched& S, const Epi& E) {
;     ...
; #pragma unroll
;         for (int a = 0; a < 2; ++a)
; #pragma unroll
;             for (int b = 0; b < 2; ++b)
; #pragma unroll
;                 for (int m = 0; m < 4; ++m)
; #pragma unroll
;                     for (int n = 0; n < 2; ++n) acc[a][b][m][n] = (f32x4){0.f, 0.f, 0.f, 0.f};
.LBB0_638:
	v_mov_b32_e32 v135, 0
	v_mov_b32_e32 v134, v135
	v_mov_b64_e32 v[132:133], 0
	v_mov_b64_e32 v[130:131], 0
	v_mov_b64_e32 v[128:129], 0
	v_mov_b64_e32 v[118:119], 0
	v_mov_b64_e32 v[116:117], 0
	v_mov_b64_e32 v[114:115], 0
	v_mov_b64_e32 v[112:113], 0
	v_mov_b64_e32 v[94:95], 0
	v_mov_b64_e32 v[92:93], 0
	v_mov_b64_e32 v[90:91], 0
	v_mov_b64_e32 v[88:89], 0
	v_mov_b64_e32 v[78:79], 0
	v_mov_b64_e32 v[76:77], 0
	v_mov_b64_e32 v[74:75], 0
	v_mov_b64_e32 v[72:73], 0
	v_mov_b64_e32 v[126:127], 0
	v_mov_b64_e32 v[124:125], 0
	v_mov_b64_e32 v[122:123], 0
	v_mov_b64_e32 v[120:121], 0
	v_mov_b64_e32 v[110:111], 0
	v_mov_b64_e32 v[108:109], 0
	v_mov_b64_e32 v[106:107], 0
	v_mov_b64_e32 v[104:105], 0
	v_mov_b64_e32 v[86:87], 0
	v_mov_b64_e32 v[84:85], 0
	v_mov_b64_e32 v[82:83], 0
	v_mov_b64_e32 v[80:81], 0
	v_mov_b64_e32 v[70:71], 0
	v_mov_b64_e32 v[68:69], 0
	v_mov_b64_e32 v[66:67], 0
	v_mov_b64_e32 v[64:65], 0
	v_mov_b64_e32 v[62:63], 0
	v_mov_b64_e32 v[60:61], 0
	v_mov_b64_e32 v[58:59], 0
	v_mov_b64_e32 v[56:57], 0
	v_mov_b64_e32 v[46:47], 0
	v_mov_b64_e32 v[44:45], 0
	v_mov_b64_e32 v[42:43], 0
	v_mov_b64_e32 v[40:41], 0
	v_mov_b64_e32 v[30:31], 0
	v_mov_b64_e32 v[28:29], 0
	v_mov_b64_e32 v[26:27], 0
	v_mov_b64_e32 v[24:25], 0
	v_mov_b64_e32 v[14:15], 0
	v_mov_b64_e32 v[12:13], 0
	v_mov_b64_e32 v[10:11], 0
	v_mov_b64_e32 v[8:9], 0
	v_mov_b64_e32 v[54:55], 0
	v_mov_b64_e32 v[52:53], 0
	v_mov_b64_e32 v[50:51], 0
	v_mov_b64_e32 v[48:49], 0
	v_mov_b64_e32 v[38:39], 0
	v_mov_b64_e32 v[36:37], 0
	v_mov_b64_e32 v[34:35], 0
	v_mov_b64_e32 v[32:33], 0
	v_mov_b64_e32 v[22:23], 0
	v_mov_b64_e32 v[20:21], 0
	v_mov_b64_e32 v[18:19], 0
	v_mov_b64_e32 v[16:17], 0
	v_mov_b64_e32 v[6:7], 0
	v_mov_b64_e32 v[4:5], 0
	v_mov_b64_e32 v[2:3], 0
	v_mov_b64_e32 v[0:1], 0
	s_and_b64 vcc, exec, s[60:61]
	s_cbranch_vccnz .LBB0_587
	s_branch .LBB0_588

; template <class Epi, bool ALIGN_EPI, bool SP2>
; __device__ __forceinline__ void gemm_phase(LAS unsigned char* lds, const Gemm g, const Sched& S, const Epi& E) {
;     ...
; #pragma unroll
;         for (int a = 0; a < 2; ++a)
; #pragma unroll
;             for (int b = 0; b < 2; ++b)
; #pragma unroll
;                 for (int m = 0; m < 4; ++m)
; #pragma unroll
;                     for (int n = 0; n < 2; ++n) acc[a][b][m][n] = (f32x4){0.f, 0.f, 0.f, 0.f};
.LBB0_775:
	s_add_i32 s17, s66, -2
	s_add_u32 s46, s46, 0x100
	v_mov_b32_e32 v0, 0
	s_addc_u32 s47, s47, 0
	s_mov_b32 s22, 0
	v_mov_b32_e32 v1, v0
	v_mov_b64_e32 v[2:3], 0
	v_mov_b64_e32 v[4:5], 0
	v_mov_b64_e32 v[6:7], 0
	v_mov_b64_e32 v[16:17], 0
	v_mov_b64_e32 v[18:19], 0
	v_mov_b64_e32 v[20:21], 0
	v_mov_b64_e32 v[22:23], 0
	v_mov_b64_e32 v[32:33], 0
	v_mov_b64_e32 v[34:35], 0
	v_mov_b64_e32 v[36:37], 0
	v_mov_b64_e32 v[38:39], 0
	v_mov_b64_e32 v[48:49], 0
	v_mov_b64_e32 v[50:51], 0
	v_mov_b64_e32 v[52:53], 0
	v_mov_b64_e32 v[54:55], 0
	v_mov_b64_e32 v[8:9], 0
	v_mov_b64_e32 v[10:11], 0
	v_mov_b64_e32 v[12:13], 0
	v_mov_b64_e32 v[14:15], 0
	v_mov_b64_e32 v[24:25], 0
	v_mov_b64_e32 v[26:27], 0
	v_mov_b64_e32 v[28:29], 0
	v_mov_b64_e32 v[30:31], 0
	v_mov_b64_e32 v[40:41], 0
	v_mov_b64_e32 v[42:43], 0
	v_mov_b64_e32 v[44:45], 0
	v_mov_b64_e32 v[46:47], 0
	v_mov_b64_e32 v[56:57], 0
	v_mov_b64_e32 v[58:59], 0
	v_mov_b64_e32 v[60:61], 0
	v_mov_b64_e32 v[62:63], 0
	v_mov_b64_e32 v[64:65], 0
	v_mov_b64_e32 v[66:67], 0
	v_mov_b64_e32 v[68:69], 0
	v_mov_b64_e32 v[70:71], 0
	v_mov_b64_e32 v[80:81], 0
	v_mov_b64_e32 v[82:83], 0
	v_mov_b64_e32 v[84:85], 0
	v_mov_b64_e32 v[86:87], 0
	v_mov_b64_e32 v[102:103], 0
	v_mov_b64_e32 v[104:105], 0
	v_mov_b64_e32 v[106:107], 0
	v_mov_b64_e32 v[108:109], 0
	v_mov_b64_e32 v[118:119], 0
	v_mov_b64_e32 v[120:121], 0
	v_mov_b64_e32 v[122:123], 0
	v_mov_b64_e32 v[124:125], 0
	v_mov_b64_e32 v[72:73], 0
	v_mov_b64_e32 v[74:75], 0
	v_mov_b64_e32 v[76:77], 0
	v_mov_b64_e32 v[78:79], 0
	v_mov_b64_e32 v[88:89], 0
	v_mov_b64_e32 v[90:91], 0
	v_mov_b64_e32 v[92:93], 0
	v_mov_b64_e32 v[94:95], 0
	v_mov_b64_e32 v[110:111], 0
	v_mov_b64_e32 v[112:113], 0
	v_mov_b64_e32 v[114:115], 0
	v_mov_b64_e32 v[116:117], 0
	v_mov_b64_e32 v[126:127], 0
	v_mov_b64_e32 v[128:129], 0
	v_mov_b64_e32 v[130:131], 0
	v_mov_b64_e32 v[132:133], 0
